# retention: deeper LDS read-ahead - S phase keeps 11 K fragments in flight (V-fragment/V-address registers are idle there), O phase keeps 8 V fragments in flight (K-fragment registers are idle there)
# speedup vs baseline: 1.0034x; 1.0026x over previous
; #define LAS __attribute__((address_space(3)))
; #define RT_DMA_K(kt_, bf_, i_) __builtin_amdgcn_raw_ptr_buffer_load_lds(RK, (LAS void*)(lds + RT_K0 + (bf_) * 32768 + (w + 8 * (i_)) * 1024), 16, (int)RT_KOFF, (int)((unsigned)((b * SEQ + (kt_) * 64) * DR + h * 256) * 2u + (i_) * 65536u), 0, 0)
; #define RT_DMA_V(kt_, bf_, i_) __builtin_amdgcn_raw_ptr_buffer_load_lds(RV, (LAS void*)(lds + RT_V0 + (bf_) * 32768 + (w + 8 * (i_)) * 1024), 16, (int)RT_VOFF, (int)((unsigned)((h * 256) * MTOK + b * SEQ + (kt_) * 64) * 2u + (i_) * 1048576u), 0, 0)
; #define RT_KRD(dst, s0) do { _Pragma("unroll") for (int j_ = 0; j_ < 2; ++j_) dst[j_] = *(const LAS bf16x8*)(kb + ((((2 * ((s0) + j_)) | hh) ^ x15) << 4)); } while (0)
; #define RT_KMM(src, s0) do { _Pragma("unroll") for (int j_ = 0; j_ < 2; ++j_) st = __builtin_amdgcn_mfma_f32_32x32x16_bf16(src[j_], qf[(s0) + j_], st, 0, 0, 0); } while (0)
; __device__ __forceinline__ void p2_ret(const Frame& F, ArgsP a, int layer) {
;     ...
;                 { const LAS unsigned char* kb = lds + RT_K0 + bf * 32768 + (32 * wc + kap) * 512;
;     ...
;                   bf16x8 ka[2], kd[2], kc[2];
;                   RT_KRD(ka, 0); RT_KRD(kd, 2); __builtin_amdgcn_sched_barrier(0);
;                   RT_KRD(kc, 4); RT_KMM(ka, 0); if (pre) { RT_DMA_K(kt + 1, bf ^ 1, 0); RT_DMA_V(kt + 1, bf ^ 1, 0); } __builtin_amdgcn_sched_barrier(0);
;                   RT_KRD(ka, 6); RT_KMM(kd, 2); __builtin_amdgcn_sched_barrier(0);
;                   RT_KRD(kd, 8); RT_KMM(kc, 4); if (pre) { RT_DMA_K(kt + 1, bf ^ 1, 1); RT_DMA_V(kt + 1, bf ^ 1, 1); } __builtin_amdgcn_sched_barrier(0);
;                   RT_KRD(kc, 10); RT_KMM(ka, 6); __builtin_amdgcn_sched_barrier(0);
;                   RT_KRD(ka, 12); RT_KMM(kd, 8); if (pre) { RT_DMA_K(kt + 1, bf ^ 1, 2); RT_DMA_V(kt + 1, bf ^ 1, 2); } __builtin_amdgcn_sched_barrier(0);
;                   RT_KRD(kd, 14); RT_KMM(kc, 10); __builtin_amdgcn_sched_barrier(0);
;                   RT_KMM(ka, 12); if (pre) { RT_DMA_K(kt + 1, bf ^ 1, 3); RT_DMA_V(kt + 1, bf ^ 1, 3); } __builtin_amdgcn_sched_barrier(0);
;                   RT_KMM(kd, 14); __builtin_amdgcn_sched_barrier(0);
.LBB0_383:
	v_mov_b32_e32 v0, v207
	s_and_b32 s6, s31, 0x8000
	v_lshlrev_b32_e32 v99, 1, v0
	v_lshrrev_b32_e32 v100, 1, v0
	v_and_b32_e32 v98, 19, v0
	v_and_b32_e32 v99, 8, v99
	v_and_b32_e32 v100, 4, v100
	v_or3_b32 v115, v99, v98, v100
	v_ashrrev_i32_e32 v116, 5, v0
	s_add_i32 s4, s6, 0
	v_or_b32_e32 v98, s80, v115
	v_lshl_add_u32 v227, v98, 9, s4
	v_bitop3_b32 v228, v115, v116, 15 bitop3:0x6c
	v_lshl_add_u32 v228, v228, 4, v227
	ds_read_b128 v[98:101], v228
	v_or_b32_e32 v229, 2, v116
	v_bitop3_b32 v229, v115, v229, 15 bitop3:0x6c
	v_lshl_add_u32 v229, v229, 4, v227
	ds_read_b128 v[190:193], v229
	v_or_b32_e32 v230, 4, v116
	v_bitop3_b32 v230, v115, v230, 15 bitop3:0x6c
	v_lshl_add_u32 v230, v230, 4, v227
	ds_read_b128 v[194:197], v230
	v_or_b32_e32 v231, 6, v116
	v_bitop3_b32 v231, v115, v231, 15 bitop3:0x6c
	v_lshl_add_u32 v231, v231, 4, v227
	ds_read_b128 v[198:201], v231
	v_or_b32_e32 v250, 8, v116
	v_bitop3_b32 v250, v115, v250, 15 bitop3:0x6c
	v_lshl_add_u32 v250, v250, 4, v227
	ds_read_b128 v[202:205], v250
	v_or_b32_e32 v251, 10, v116
	v_bitop3_b32 v251, v115, v251, 15 bitop3:0x6c
	v_lshl_add_u32 v251, v251, 4, v227
	ds_read_b128 v[212:215], v251
	v_or_b32_e32 v252, 12, v116
	v_bitop3_b32 v252, v115, v252, 15 bitop3:0x6c
	v_lshl_add_u32 v252, v252, 4, v227
	ds_read_b128 v[216:219], v252
	v_or_b32_e32 v253, 14, v116
	v_bitop3_b32 v253, v115, v253, 15 bitop3:0x6c
	v_lshl_add_u32 v253, v253, 4, v227
	ds_read_b128 v[234:237], v253
	ds_read_b128 v[238:241], v228 offset:256
	ds_read_b128 v[242:245], v229 offset:256
	ds_read_b128 v[246:249], v230 offset:256
	v_and_b32_e32 v117, 31, v0
	s_xor_b32 s4, s6, 0x8000
	s_add_i32 s5, s22, s4
	s_add_i32 s7, s25, s30
	s_add_i32 m0, s33, s4
	s_add_i32 s12, s7, 0x80
	s_mov_b32 s46, s42
	s_mov_b32 s47, s43
	buffer_load_dwordx4 v225, s[44:47], s12 offen lds
	s_waitcnt lgkmcnt(10)
	v_mfma_f32_32x32x16_bf16 v[98:113], v[98:101], v[118:121], 0
	s_waitcnt lgkmcnt(9)
	v_mfma_f32_32x32x16_bf16 v[98:113], v[190:193], v[122:125], v[98:113]
	ds_read_b128 v[190:193], v231 offset:256
	s_waitcnt lgkmcnt(9)
	v_mfma_f32_32x32x16_bf16 v[98:113], v[194:197], v[126:129], v[98:113]
	ds_read_b128 v[194:197], v250 offset:256
	s_waitcnt lgkmcnt(9)
	v_mfma_f32_32x32x16_bf16 v[98:113], v[198:201], v[130:133], v[98:113]
	ds_read_b128 v[198:201], v251 offset:256
	s_add_i32 s4, s4, 0x10000
	s_add_i32 m0, s4, s24
	s_add_i32 s12, s7, 0x100080
	buffer_load_dwordx4 v225, s[44:47], s12 offen lds
	s_waitcnt lgkmcnt(9)
	v_mfma_f32_32x32x16_bf16 v[98:113], v[202:205], v[134:137], v[98:113]
	ds_read_b128 v[202:205], v252 offset:256
	s_waitcnt lgkmcnt(9)
	v_mfma_f32_32x32x16_bf16 v[98:113], v[212:215], v[138:141], v[98:113]
	ds_read_b128 v[212:215], v253 offset:256
	s_waitcnt lgkmcnt(9)
	v_mfma_f32_32x32x16_bf16 v[98:113], v[216:219], v[142:145], v[98:113]
	s_waitcnt lgkmcnt(8)
	v_mfma_f32_32x32x16_bf16 v[98:113], v[234:237], v[146:149], v[98:113]
	s_add_i32 m0, s4, s26
	s_add_i32 s12, s7, 0x200080
	buffer_load_dwordx4 v225, s[44:47], s12 offen lds
	s_waitcnt lgkmcnt(7)
	v_mfma_f32_32x32x16_bf16 v[98:113], v[238:241], v[150:153], v[98:113]
	s_waitcnt lgkmcnt(6)
	v_mfma_f32_32x32x16_bf16 v[98:113], v[242:245], v[154:157], v[98:113]
	s_waitcnt lgkmcnt(5)
	v_mfma_f32_32x32x16_bf16 v[98:113], v[246:249], v[158:161], v[98:113]
	s_waitcnt lgkmcnt(4)
	v_mfma_f32_32x32x16_bf16 v[98:113], v[190:193], v[162:165], v[98:113]
	s_add_i32 m0, s4, s28
	s_add_i32 s7, s7, 0x300080
	buffer_load_dwordx4 v225, s[44:47], s7 offen lds
	s_waitcnt lgkmcnt(3)
	v_mfma_f32_32x32x16_bf16 v[98:113], v[194:197], v[166:169], v[98:113]
	s_waitcnt lgkmcnt(2)
	v_mfma_f32_32x32x16_bf16 v[98:113], v[198:201], v[170:173], v[98:113]
	s_waitcnt lgkmcnt(1)
	v_mfma_f32_32x32x16_bf16 v[98:113], v[202:205], v[174:177], v[98:113]
	s_waitcnt lgkmcnt(0)
	v_mfma_f32_32x32x16_bf16 v[98:113], v[212:215], v[178:181], v[98:113]
	v_lshlrev_b32_e32 v250, 3, v115
	v_and_b32_e32 v250, 0x70, v250
	s_add_i32 s13, s64, s6
	v_lshl_add_u32 v251, v115, 7, s13
	v_lshlrev_b32_e32 v252, 4, v116
	s_lshl_b32 s14, s80, 1
	v_xad_u32 v246, v250, v252, v251
	v_add_u32_e32 v253, 32, v252
	v_xad_u32 v247, v250, v253, v251
	v_xor_b32_e32 v246, s14, v246
	v_xor_b32_e32 v247, s14, v247
	v_xor_b32_e32 v248, 64, v246
	v_xor_b32_e32 v249, 64, v247
	ds_read_b128 v[234:237], v246
	ds_read_b128 v[238:241], v247
	ds_read_b128 v[242:245], v246 offset:4096
	ds_read_b128 v[216:219], v247 offset:4096
	s_cmp_ge_u32 s91, s29
	s_cbranch_scc1 .Ldiag_pack
	v_cvt_pk_bf16_f32 v190, v98, v99
	v_cvt_pk_bf16_f32 v191, v100, v101
	v_cvt_pk_bf16_f32 v192, v102, v103
	v_cvt_pk_bf16_f32 v193, v104, v105
	v_cvt_pk_bf16_f32 v194, v106, v107
	v_cvt_pk_bf16_f32 v195, v108, v109
	v_cvt_pk_bf16_f32 v196, v110, v111
	v_cvt_pk_bf16_f32 v197, v112, v113
; #define LAS __attribute__((address_space(3)))
; #define RT_VRD(dst, g) do { _Pragma("unroll") for (int j_ = 0; j_ < 2; ++j_) { const int jj_ = 2 * ((g) & 1) + j_; dst[j_] = *(const LAS bf16x8*)(vb + ((g) >> 1) * 4096 + (((4 * (jj_ >> 1) + 2 * (jj_ & 1) + hh) << 4) ^ m4)); } } while (0)
; #define RT_VMM(src, g) do { _Pragma("unroll") for (int j_ = 0; j_ < 2; ++j_) { const int jj_ = 2 * ((g) & 1) + j_; oacc[(g) >> 1] = __builtin_amdgcn_mfma_f32_32x32x16_bf16(src[j_], pf[jj_ >> 1][jj_ & 1], oacc[(g) >> 1], 0, 0, 0); } } while (0)
; __device__ __forceinline__ void p2_ret(const Frame& F, ArgsP a, int layer) {
;     ...
;                 { bf16x8 pf[2][2];
; #pragma unroll
;                   for (int kb2 = 0; kb2 < 2; ++kb2)
; #pragma unroll
;                       for (int s = 0; s < 2; ++s) pf[kb2][s] = *(const LAS bf16x8*)(lds + RT_P + ((wr * 2 + kb2) * 2 + s) * 1024 + lane * 16);
;                   const LAS unsigned char* vb = lds + RT_V0 + bf * 32768 + (128 * wc + kap) * 128;
;     ...
;                   bf16x8 va[2], vc[2];
;                   RT_VRD(va, 0); __builtin_amdgcn_sched_barrier(0);
;                   RT_VRD(vc, 1); RT_VMM(va, 0); __builtin_amdgcn_sched_barrier(0);
;                   RT_VRD(va, 2); RT_VMM(vc, 1); __builtin_amdgcn_sched_barrier(0);
;                   RT_VRD(vc, 3); RT_VMM(va, 2); __builtin_amdgcn_sched_barrier(0);
;                   RT_VRD(va, 4); RT_VMM(vc, 3); __builtin_amdgcn_sched_barrier(0);
;                   RT_VRD(vc, 5); RT_VMM(va, 4); __builtin_amdgcn_sched_barrier(0);
;                   RT_VRD(va, 6); RT_VMM(vc, 5); __builtin_amdgcn_sched_barrier(0);
;                   RT_VRD(vc, 7); RT_VMM(va, 6); __builtin_amdgcn_sched_barrier(0);
;                   RT_VMM(vc, 7); __builtin_amdgcn_sched_barrier(0);
.LBB0_387:
	s_nop 6
	v_lshlrev_b32_e32 v98, 4, v0
	v_add_u32_e32 v99, s83, v98
	ds_write_b128 v99, v[190:193]
	ds_write_b128 v99, v[194:197] offset:1024
	s_lshl_b32 s12, s80, 6
	s_sub_i32 s12, 0x800, s12
	s_add_i32 s12, s12, s82
	v_add_u32_e32 v250, s12, v98
	ds_read_b128 v[198:201], v246 offset:8192
	ds_read_b128 v[202:205], v247 offset:8192
	ds_read_b128 v[212:215], v246 offset:12288
	ds_read_b128 v[106:109], v247 offset:12288
	s_waitcnt lgkmcnt(9)
	v_mfma_f32_32x32x16_bf16 v[82:97], v[234:237], v[190:193], v[82:97]
	s_waitcnt lgkmcnt(8)
	v_mfma_f32_32x32x16_bf16 v[82:97], v[238:241], v[194:197], v[82:97]
	ds_read_b128 v[234:237], v248
	ds_read_b128 v[238:241], v249
	s_waitcnt lgkmcnt(9)
	v_mfma_f32_32x32x16_bf16 v[66:81], v[242:245], v[190:193], v[66:81]
	s_waitcnt lgkmcnt(8)
	v_mfma_f32_32x32x16_bf16 v[66:81], v[216:219], v[194:197], v[66:81]
	ds_read_b128 v[242:245], v248 offset:4096
	ds_read_b128 v[216:219], v249 offset:4096
	s_waitcnt lgkmcnt(7)
	v_mfma_f32_32x32x16_bf16 v[50:65], v[198:201], v[190:193], v[50:65]
	s_waitcnt lgkmcnt(6)
	v_mfma_f32_32x32x16_bf16 v[50:65], v[202:205], v[194:197], v[50:65]
	ds_read_b128 v[198:201], v248 offset:8192
	ds_read_b128 v[202:205], v249 offset:8192
	s_barrier
	ds_read_b128 v[98:101], v250
	ds_read_b128 v[102:105], v250 offset:1024
	s_add_i32 s12, s30, 0x80
	s_cmp_eq_u32 s12, s11
	s_cbranch_scc1 .Lrk_skip
	s_add_i32 s13, s22, s6
	s_mov_b32 m0, s13
	s_add_i32 s12, s27, 0x10000
	buffer_load_dwordx4 v224, s[40:43], s12 offen lds
	s_add_i32 m0, s13, 0x2000
	s_add_i32 s12, s27, 0x20000
	buffer_load_dwordx4 v224, s[40:43], s12 offen lds
	s_add_i32 m0, s13, 0x4000
	s_add_i32 s12, s27, 0x30000
	buffer_load_dwordx4 v224, s[40:43], s12 offen lds
	s_add_i32 m0, s13, 0x6000
	s_add_i32 s12, s27, 0x40000
	buffer_load_dwordx4 v224, s[40:43], s12 offen lds
.Lrk_skip:
	s_waitcnt lgkmcnt(9)
	v_mfma_f32_32x32x16_bf16 v[34:49], v[212:215], v[190:193], v[34:49]
	s_waitcnt lgkmcnt(8)
	v_mfma_f32_32x32x16_bf16 v[34:49], v[106:109], v[194:197], v[34:49]
	ds_read_b128 v[212:215], v248 offset:12288
	ds_read_b128 v[106:109], v249 offset:12288
	s_waitcnt lgkmcnt(3)
	v_mfma_f32_32x32x16_bf16 v[82:97], v[234:237], v[98:101], v[82:97]
	s_waitcnt lgkmcnt(2)
	v_mfma_f32_32x32x16_bf16 v[82:97], v[238:241], v[102:105], v[82:97]
	v_mfma_f32_32x32x16_bf16 v[66:81], v[242:245], v[98:101], v[66:81]
	v_mfma_f32_32x32x16_bf16 v[66:81], v[216:219], v[102:105], v[66:81]
	v_mfma_f32_32x32x16_bf16 v[50:65], v[198:201], v[98:101], v[50:65]
	v_mfma_f32_32x32x16_bf16 v[50:65], v[202:205], v[102:105], v[50:65]
	s_waitcnt lgkmcnt(1)
	v_mfma_f32_32x32x16_bf16 v[34:49], v[212:215], v[98:101], v[34:49]
	s_waitcnt lgkmcnt(0)
	v_mfma_f32_32x32x16_bf16 v[34:49], v[106:109], v[102:105], v[34:49]
	s_add_i32 s12, s30, 0x80
	s_cmp_eq_u32 s12, s11
	s_cbranch_scc1 .Lrk_w0
	s_waitcnt vmcnt(4)
	s_branch .Lrk_wd
